# grid barrier: non-leader workgroups poll the top-level generation word directly (one forwarding hop less per barrier)
# speedup vs baseline: 1.0071x; 1.0033x over previous
; __device__ __forceinline__ unsigned xb_ld(unsigned* p)              { return __hip_atomic_load(p, __ATOMIC_RELAXED, __HIP_MEMORY_SCOPE_AGENT); }
; __device__ __forceinline__ unsigned xb_add(unsigned* p, unsigned v) { return __hip_atomic_fetch_add(p, v, __ATOMIC_RELAXED, __HIP_MEMORY_SCOPE_AGENT); }
; #define XB_SPIN(cond, bar) do { unsigned _sp = 0; while (cond) { __builtin_amdgcn_s_sleep(1); \
;     if ((++_sp & 255u) == 0u) { if (xb_ld(&(bar)[XB_TMO])) break; if (_sp > XB_SPIN_CAP) { atomicAdd(&(bar)[XB_TMO], 1u); break; } } } } while (0)
; __device__ __forceinline__ void xcd_barrier(const XcdBarrier& b) {
;     ...
;         const unsigned old = xb_add(&bar[XB_XSUB(b.x)], 1u);
;         const unsigned gen = old / nloc;
;         if (old + 1u == (gen + 1u) * nloc) {
;             __builtin_amdgcn_fence(__ATOMIC_RELEASE, "agent");
;             asm volatile("s_waitcnt vmcnt(0)" ::: "memory");
;             const unsigned og = xb_add(&bar[XB_TOP], 1u);
;             const unsigned tg = og / nx;
;             if (og + 1u == (tg + 1u) * nx) xb_add(&bar[XB_TOPGEN], 1u);
;             else XB_SPIN(xb_ld(&bar[XB_TOPGEN]) == tg, bar);
;             __builtin_amdgcn_fence(__ATOMIC_ACQUIRE, "agent");
;             xb_add(&bar[XB_XGEN(b.x)], 1u);
;             asm volatile("s_waitcnt vmcnt(0)" ::: "memory");
;         } else {
;             XB_SPIN(xb_ld(&bar[XB_XGEN(b.x)]) == gen, bar);
;             __builtin_amdgcn_fence(__ATOMIC_ACQUIRE, "agent");
.LBB0_120:
	s_or_b64 exec, exec, s[6:7]
	v_cvt_f32_u32_e32 v5, v3
	s_waitcnt vmcnt(0)
	v_readfirstlane_b32 s4, v4
	v_sub_u32_e32 v4, 0, v3
	v_rcp_iflag_f32_e32 v5, v5
	v_add_u32_e32 v6, s4, v2
	v_mul_f32_e32 v5, 0x4f7ffffe, v5
	v_cvt_u32_f32_e32 v5, v5
	v_mul_lo_u32 v2, v4, v5
	v_mul_hi_u32 v2, v5, v2
	v_add_u32_e32 v2, v5, v2
	v_mul_hi_u32 v2, v6, v2
	v_mul_lo_u32 v4, v2, v3
	v_sub_u32_e32 v4, v6, v4
	v_add_u32_e32 v5, 1, v2
	v_cmp_ge_u32_e32 vcc, v4, v3
	s_nop 1
	v_cndmask_b32_e32 v2, v2, v5, vcc
	v_sub_u32_e32 v5, v4, v3
	v_cndmask_b32_e32 v4, v4, v5, vcc
	v_add_u32_e32 v5, 1, v2
	v_cmp_ge_u32_e32 vcc, v4, v3
	v_add_u32_e32 v4, 1, v6
	s_nop 0
	v_cndmask_b32_e32 v2, v2, v5, vcc
	v_mul_lo_u32 v5, v3, v2
	v_add_u32_e32 v3, v5, v3
	v_cmp_ne_u32_e32 vcc, v4, v3
	s_and_saveexec_b64 s[4:5], vcc
	s_xor_b64 s[4:5], exec, s[4:5]
	s_cbranch_execz .LBB0_134
	s_waitcnt lgkmcnt(0)
	s_add_u32 s10, s62, 0x7500
	s_addc_u32 s11, s63, 0
	v_mov_b32_e32 v1, 0
	global_load_dword v1, v1, s[10:11] sc1
	s_waitcnt vmcnt(0)
	v_cmp_eq_u32_e32 vcc, v1, v2
	s_and_saveexec_b64 s[6:7], vcc
	s_cbranch_execz .LBB0_133
	s_add_u32 s8, s62, 0x4200
	s_addc_u32 s9, s63, 0
	s_mov_b32 s24, 1
	s_mov_b64 s[12:13], 0
	v_mov_b32_e32 v1, 0
	s_branch .LBB0_124

; __device__ __forceinline__ unsigned xb_ld(unsigned* p)              { return __hip_atomic_load(p, __ATOMIC_RELAXED, __HIP_MEMORY_SCOPE_AGENT); }
; __device__ __forceinline__ unsigned xb_add(unsigned* p, unsigned v) { return __hip_atomic_fetch_add(p, v, __ATOMIC_RELAXED, __HIP_MEMORY_SCOPE_AGENT); }
; #define XB_SPIN(cond, bar) do { unsigned _sp = 0; while (cond) { __builtin_amdgcn_s_sleep(1); \
;     if ((++_sp & 255u) == 0u) { if (xb_ld(&(bar)[XB_TMO])) break; if (_sp > XB_SPIN_CAP) { atomicAdd(&(bar)[XB_TMO], 1u); break; } } } } while (0)
; __device__ __forceinline__ void xcd_barrier(const XcdBarrier& b) {
;     ...
;         const unsigned old = xb_add(&bar[XB_XSUB(b.x)], 1u);
;         const unsigned gen = old / nloc;
;         if (old + 1u == (gen + 1u) * nloc) {
;             __builtin_amdgcn_fence(__ATOMIC_RELEASE, "agent");
;             asm volatile("s_waitcnt vmcnt(0)" ::: "memory");
;             const unsigned og = xb_add(&bar[XB_TOP], 1u);
;             const unsigned tg = og / nx;
;             if (og + 1u == (tg + 1u) * nx) xb_add(&bar[XB_TOPGEN], 1u);
;             else XB_SPIN(xb_ld(&bar[XB_TOPGEN]) == tg, bar);
;             __builtin_amdgcn_fence(__ATOMIC_ACQUIRE, "agent");
;             xb_add(&bar[XB_XGEN(b.x)], 1u);
;             asm volatile("s_waitcnt vmcnt(0)" ::: "memory");
;         } else {
;             XB_SPIN(xb_ld(&bar[XB_XGEN(b.x)]) == gen, bar);
;             __builtin_amdgcn_fence(__ATOMIC_ACQUIRE, "agent");
.LBB0_340:
	s_or_b64 exec, exec, s[6:7]
	v_cvt_f32_u32_e32 v5, v3
	s_waitcnt vmcnt(0)
	v_readfirstlane_b32 s4, v4
	v_sub_u32_e32 v4, 0, v3
	v_rcp_iflag_f32_e32 v5, v5
	v_add_u32_e32 v6, s4, v2
	v_mul_f32_e32 v5, 0x4f7ffffe, v5
	v_cvt_u32_f32_e32 v5, v5
	v_mul_lo_u32 v2, v4, v5
	v_mul_hi_u32 v2, v5, v2
	v_add_u32_e32 v2, v5, v2
	v_mul_hi_u32 v2, v6, v2
	v_mul_lo_u32 v4, v2, v3
	v_sub_u32_e32 v4, v6, v4
	v_add_u32_e32 v5, 1, v2
	v_cmp_ge_u32_e32 vcc, v4, v3
	s_nop 1
	v_cndmask_b32_e32 v2, v2, v5, vcc
	v_sub_u32_e32 v5, v4, v3
	v_cndmask_b32_e32 v4, v4, v5, vcc
	v_add_u32_e32 v5, 1, v2
	v_cmp_ge_u32_e32 vcc, v4, v3
	v_add_u32_e32 v4, 1, v6
	s_nop 0
	v_cndmask_b32_e32 v2, v2, v5, vcc
	v_mul_lo_u32 v5, v3, v2
	v_add_u32_e32 v3, v5, v3
	v_cmp_ne_u32_e32 vcc, v4, v3
	s_and_saveexec_b64 s[4:5], vcc
	s_xor_b64 s[4:5], exec, s[4:5]
	s_cbranch_execz .LBB0_354
	s_waitcnt lgkmcnt(0)
	s_add_u32 s10, s62, 0x7500
	s_addc_u32 s11, s63, 0
	v_mov_b32_e32 v1, 0
	global_load_dword v1, v1, s[10:11] sc1
	s_waitcnt vmcnt(0)
	v_cmp_eq_u32_e32 vcc, v1, v2
	s_and_saveexec_b64 s[6:7], vcc
	s_cbranch_execz .LBB0_353
	s_add_u32 s8, s62, 0x4200
	s_addc_u32 s9, s63, 0
	s_mov_b32 s22, 1
	s_mov_b64 s[12:13], 0
	v_mov_b32_e32 v1, 0
	s_branch .LBB0_344

; __device__ __forceinline__ unsigned xb_ld(unsigned* p)              { return __hip_atomic_load(p, __ATOMIC_RELAXED, __HIP_MEMORY_SCOPE_AGENT); }
; __device__ __forceinline__ unsigned xb_add(unsigned* p, unsigned v) { return __hip_atomic_fetch_add(p, v, __ATOMIC_RELAXED, __HIP_MEMORY_SCOPE_AGENT); }
; #define XB_SPIN(cond, bar) do { unsigned _sp = 0; while (cond) { __builtin_amdgcn_s_sleep(1); \
;     if ((++_sp & 255u) == 0u) { if (xb_ld(&(bar)[XB_TMO])) break; if (_sp > XB_SPIN_CAP) { atomicAdd(&(bar)[XB_TMO], 1u); break; } } } } while (0)
; __device__ __forceinline__ void xcd_barrier(const XcdBarrier& b) {
;     ...
;         const unsigned old = xb_add(&bar[XB_XSUB(b.x)], 1u);
;         const unsigned gen = old / nloc;
;         if (old + 1u == (gen + 1u) * nloc) {
;             __builtin_amdgcn_fence(__ATOMIC_RELEASE, "agent");
;             asm volatile("s_waitcnt vmcnt(0)" ::: "memory");
;             const unsigned og = xb_add(&bar[XB_TOP], 1u);
;             const unsigned tg = og / nx;
;             if (og + 1u == (tg + 1u) * nx) xb_add(&bar[XB_TOPGEN], 1u);
;             else XB_SPIN(xb_ld(&bar[XB_TOPGEN]) == tg, bar);
;             __builtin_amdgcn_fence(__ATOMIC_ACQUIRE, "agent");
;             xb_add(&bar[XB_XGEN(b.x)], 1u);
;             asm volatile("s_waitcnt vmcnt(0)" ::: "memory");
;         } else {
;             XB_SPIN(xb_ld(&bar[XB_XGEN(b.x)]) == gen, bar);
;             __builtin_amdgcn_fence(__ATOMIC_ACQUIRE, "agent");
.LBB0_842:
	s_or_b64 exec, exec, s[6:7]
	v_cvt_f32_u32_e32 v5, v3
	s_waitcnt vmcnt(0)
	v_readfirstlane_b32 s4, v4
	v_sub_u32_e32 v4, 0, v3
	v_rcp_iflag_f32_e32 v5, v5
	v_add_u32_e32 v6, s4, v2
	v_mul_f32_e32 v5, 0x4f7ffffe, v5
	v_cvt_u32_f32_e32 v5, v5
	v_mul_lo_u32 v2, v4, v5
	v_mul_hi_u32 v2, v5, v2
	v_add_u32_e32 v2, v5, v2
	v_mul_hi_u32 v2, v6, v2
	v_mul_lo_u32 v4, v2, v3
	v_sub_u32_e32 v4, v6, v4
	v_add_u32_e32 v5, 1, v2
	v_cmp_ge_u32_e32 vcc, v4, v3
	s_nop 1
	v_cndmask_b32_e32 v2, v2, v5, vcc
	v_sub_u32_e32 v5, v4, v3
	v_cndmask_b32_e32 v4, v4, v5, vcc
	v_add_u32_e32 v5, 1, v2
	v_cmp_ge_u32_e32 vcc, v4, v3
	v_add_u32_e32 v4, 1, v6
	s_nop 0
	v_cndmask_b32_e32 v2, v2, v5, vcc
	v_mul_lo_u32 v5, v3, v2
	v_add_u32_e32 v3, v5, v3
	v_cmp_ne_u32_e32 vcc, v4, v3
	s_and_saveexec_b64 s[4:5], vcc
	s_xor_b64 s[4:5], exec, s[4:5]
	s_cbranch_execz .LBB0_856
	s_waitcnt lgkmcnt(0)
	s_add_u32 s12, s62, 0x7500
	s_addc_u32 s13, s63, 0
	v_mov_b32_e32 v1, 0
	global_load_dword v1, v1, s[12:13] sc1
	s_waitcnt vmcnt(0)
	v_cmp_eq_u32_e32 vcc, v1, v2
	s_and_saveexec_b64 s[6:7], vcc
	s_cbranch_execz .LBB0_855
	s_add_u32 s10, s62, 0x4200
	s_addc_u32 s11, s63, 0
	s_mov_b32 s24, 1
	s_mov_b64 s[14:15], 0
	v_mov_b32_e32 v1, 0
	s_branch .LBB0_846
